# v83 + streaming hint on the attention query-fragment loads + write-through on the gate-prep decay-vector store
# baseline (speedup 1.0000x reference)
.LBB0_315:
	s_or_b64 exec, exec, s[64:65]
	s_lshl_b32 s56, s68, 6
	s_or_b32 s55, s56, s55
	s_or_b32 s64, s55, s49
	s_ashr_i32 s65, s64, 31
	s_and_saveexec_b64 s[66:67], s[12:13]
	s_cbranch_execz .LBB0_317
	ds_read_b32 v2, v40 offset:65520
	s_lshl_b64 s[68:69], s[64:65], 10
	s_add_u32 s68, s62, s68
	s_addc_u32 s69, s63, s69
	v_lshl_add_u64 v[0:1], v[16:17], 2, s[68:69]
	s_waitcnt lgkmcnt(0)
	v_mul_f32_e32 v2, 0x3fb8aa3b, v2
	v_exp_f32_e32 v2, v2
	v_add_co_u32_e32 v0, vcc, 0x19700000, v0
	s_nop 1
	v_addc_co_u32_e32 v1, vcc, 0, v1, vcc
	global_store_dword v[0:1], v2, off sc0 sc1

.LBB0_372:
	s_or_b64 exec, exec, s[42:43]
	s_or_b32 s42, s49, s80
	s_or_b32 s64, s42, s33
	s_ashr_i32 s65, s64, 31
	s_and_saveexec_b64 s[42:43], s[12:13]
	s_cbranch_execz .LBB0_374
	ds_read_b32 v1, v39 offset:65520
	s_lshl_b64 s[68:69], s[64:65], 10
	s_add_u32 s68, s62, s68
	s_addc_u32 s69, s63, s69
	v_lshl_add_u64 v[2:3], v[16:17], 2, s[68:69]
	s_waitcnt lgkmcnt(0)
	v_mul_f32_e32 v1, 0x3fb8aa3b, v1
	v_exp_f32_e32 v1, v1
	v_add_co_u32_e32 v2, vcc, 0x19700000, v2
	s_nop 1
	v_addc_co_u32_e32 v3, vcc, 0, v3, vcc
	global_store_dword v[2:3], v1, off sc0 sc1

.LBB0_1333:
	s_bfe_u32 s12, s25, 0x40008
	s_lshl_b32 s10, s29, 1
	s_and_b32 s33, s10, 0xf00
	s_lshl_b32 s10, s12, 5
	s_or_b32 s36, s10, 24
	s_mov_b64 s[10:11], s[0:1]
	s_load_dwordx2 s[18:19], s[10:11], 0x80
	s_lshl_b32 s20, s12, 8
	s_mul_i32 s12, s12, 0x300000
	s_lshl_b32 s10, s30, 8
	s_or_b32 s34, s20, 0xc0
	s_and_b32 s21, s27, 0xfffff000
	s_add_u32 s35, s12, 0x240000
	s_and_b32 s39, s10, 0xf00
	s_waitcnt lgkmcnt(0)
	s_add_u32 s12, s18, 0xe600000
	s_addc_u32 s13, s19, 0
	s_lshl_b32 s10, s30, 4
	s_and_b32 s38, s10, 0xfffff000
	s_or_b32 s37, s38, s39
	s_mul_i32 s11, s37, 0x3000
	s_mul_hi_i32 s10, s37, 0x3000
	s_add_u32 s11, s12, s11
	s_addc_u32 s40, s13, s10
	s_lshl_b32 s10, s30, 3
	s_and_b32 s31, s10, 0x780
	s_lshl_b32 s41, s31, 1
	s_add_u32 s10, s11, s41
	s_addc_u32 s11, s40, 0
	s_mul_hi_i32 s40, s38, 0x3000
	s_mulk_i32 s38, 0x3000
	s_add_u32 s12, s12, s38
	s_addc_u32 s13, s13, s40
	s_add_u32 s38, s12, s41
	s_addc_u32 s40, s13, 0
	s_add_u32 s12, s38, 0x1000
	s_addc_u32 s13, s40, 0
	v_lshl_add_u64 v[2:3], s[10:11], 0, v[160:161]
	s_add_u32 s10, s38, 0x2000
	s_addc_u32 s11, s40, 0
	s_add_i32 s38, s39, 0x100
	s_lshr_b32 s38, s38, 6
	s_add_i32 s38, s38, -1
	v_lshl_add_u64 v[2:3], v[2:3], 0, v[164:165]
	s_lshl_b32 s40, s38, 6
	global_load_dwordx4 v[112:115], v[2:3], off nt
	global_load_dwordx4 v[116:119], v[2:3], off offset:32 nt
	global_load_dwordx4 v[120:123], v[2:3], off offset:64 nt
	global_load_dwordx4 v[124:127], v[2:3], off offset:96 nt
	global_load_dwordx4 v[128:131], v[2:3], off offset:128 nt
	global_load_dwordx4 v[132:135], v[2:3], off offset:160 nt
	global_load_dwordx4 v[136:139], v[2:3], off offset:192 nt
	global_load_dwordx4 v[140:143], v[2:3], off offset:224 nt
	v_add_u32_e32 v1, s40, v193
	v_mov_b64_e32 v[2:3], s[10:11]
	v_add_u32_e32 v6, s40, v194
	v_mad_i64_i32 v[4:5], s[10:11], v1, s23, v[2:3]
	v_mad_i64_i32 v[2:3], s[10:11], v6, s23, v[2:3]
	v_lshl_add_u64 v[4:5], v[4:5], 0, v[166:167]
	v_lshl_add_u64 v[2:3], v[2:3], 0, v[166:167]
	global_load_dwordx4 v[144:147], v[4:5], off
	global_load_dwordx4 v[148:151], v[2:3], off
	v_mov_b64_e32 v[2:3], s[12:13]
	v_mad_i64_i32 v[4:5], s[10:11], v1, s23, v[2:3]
	v_lshl_add_u64 v[4:5], v[4:5], 0, v[166:167]
	v_mad_i64_i32 v[2:3], s[10:11], v6, s23, v[2:3]
	v_lshl_add_u64 v[2:3], v[2:3], 0, v[166:167]
	global_load_dwordx4 v[152:155], v[4:5], off
	global_load_dwordx4 v[156:159], v[2:3], off
	v_add_u32_e32 v1, s20, v198
	v_mad_i64_i32 v[2:3], s[10:11], v1, s23, 0
	v_add_u32_e32 v1, s20, v199
	v_mad_i64_i32 v[4:5], s[10:11], v1, s23, 0
	v_mad_i64_i32 v[2:3], s[10:11], s21, v213, v[2:3]
	v_mad_i64_i32 v[4:5], s[10:11], s21, v213, v[4:5]
	v_or_b32_e32 v2, s33, v2
	v_or_b32_e32 v4, s33, v4
	s_add_i32 s39, s39, s22
	v_lshl_add_u64 v[6:7], s[18:19], 0, v[162:163]
	v_mov_b32_e32 v14, v0
	v_mov_b32_e32 v15, v0
	v_or_b32_e32 v186, s39, v187
	v_lshl_add_u64 v[188:189], v[6:7], 0, v[2:3]
	v_lshl_add_u64 v[190:191], v[6:7], 0, v[4:5]
	v_mov_b32_e32 v1, v0
	v_mov_b32_e32 v2, v0
	v_mov_b32_e32 v3, v0
	v_mov_b32_e32 v4, v0
	v_mov_b32_e32 v5, v0
	v_mov_b32_e32 v6, v0
	v_mov_b32_e32 v7, v0
	v_mov_b32_e32 v8, v0
	v_mov_b32_e32 v9, v0
	v_mov_b32_e32 v10, v0
	v_mov_b32_e32 v11, v0
	v_mov_b32_e32 v12, v0
	v_mov_b32_e32 v13, v0
	v_mov_b64_e32 v[30:31], v[14:15]
	s_waitcnt vmcnt(15)
	v_mov_b64_e32 v[46:47], v[14:15]
	s_waitcnt vmcnt(14)
	v_mov_b64_e32 v[62:63], v[14:15]
	v_mov_b64_e32 v[78:79], v[14:15]
	s_or_b32 s40, s39, 31
	v_mov_b32_e32 v169, v186
	v_mov_b32_e32 v171, 1.0
	s_mov_b64 s[20:21], 0
	v_mov_b64_e32 v[28:29], v[12:13]
	v_mov_b64_e32 v[26:27], v[10:11]
	v_mov_b64_e32 v[24:25], v[8:9]
	v_mov_b64_e32 v[22:23], v[6:7]
	v_mov_b64_e32 v[20:21], v[4:5]
	v_mov_b64_e32 v[18:19], v[2:3]
	v_mov_b64_e32 v[16:17], v[0:1]
	v_mov_b64_e32 v[44:45], v[12:13]
	v_mov_b64_e32 v[42:43], v[10:11]
	v_mov_b64_e32 v[40:41], v[8:9]
	v_mov_b64_e32 v[38:39], v[6:7]
	v_mov_b64_e32 v[36:37], v[4:5]
	v_mov_b64_e32 v[34:35], v[2:3]
	v_mov_b64_e32 v[32:33], v[0:1]
	v_mov_b64_e32 v[60:61], v[12:13]
	v_mov_b64_e32 v[58:59], v[10:11]
	v_mov_b64_e32 v[56:57], v[8:9]
	v_mov_b64_e32 v[54:55], v[6:7]
	v_mov_b64_e32 v[52:53], v[4:5]
	v_mov_b64_e32 v[50:51], v[2:3]
	v_mov_b64_e32 v[48:49], v[0:1]
	v_mov_b64_e32 v[76:77], v[12:13]
	v_mov_b64_e32 v[74:75], v[10:11]
	v_mov_b64_e32 v[72:73], v[8:9]
	v_mov_b64_e32 v[70:71], v[6:7]
	v_mov_b64_e32 v[68:69], v[4:5]
	v_mov_b64_e32 v[66:67], v[2:3]
	v_mov_b64_e32 v[64:65], v[0:1]
	s_mov_b32 s41, s38
	s_branch .LBB0_1335
